# G1-even R-row stores coalesced through LDS bounce (full 128B lines per store instr)
# speedup vs baseline: 1.0026x; 1.0026x over previous
.LBB0_243:
	v_mov_b64_e32 v[66:67], s[10:11]
	s_movk_i32 s2, 0x1400
	v_mad_i64_i32 v[66:67], s[20:21], v82, s2, v[66:67]
	s_lshl_b32 s96, s96, 1
	v_lshl_add_u64 v[66:67], v[66:67], 0, s[96:97]
	v_lshlrev_b32_e32 v146, 1, v132
	v_lshl_add_u64 v[66:67], v[66:67], 0, v[146:147]
	v_lshrrev_b32_e32 v68, 1, v0
	v_mul_u32_u24_e32 v68, 0x210, v68
	v_and_b32_e32 v71, 1, v0
	v_lshl_add_u32 v68, v71, 7, v68
	s_waitcnt lgkmcnt(11)
	v_cvt_pk_bf16_f32 v2, v2, v3
	v_cvt_pk_bf16_f32 v3, v4, v5
	s_waitcnt lgkmcnt(10)
	v_cvt_pk_bf16_f32 v4, v10, v11
	v_cvt_pk_bf16_f32 v5, v12, v13
	ds_write_b128 v68, v[2:5] offset:32
	v_cvt_pk_bf16_f32 v62, v62, v63
	v_cvt_pk_bf16_f32 v63, v64, v65
	s_waitcnt lgkmcnt(9)
	v_cvt_pk_bf16_f32 v2, v14, v15
	v_cvt_pk_bf16_f32 v3, v16, v17
	s_waitcnt lgkmcnt(8)
	v_cvt_pk_bf16_f32 v4, v22, v23
	v_cvt_pk_bf16_f32 v5, v24, v25
	ds_write_b128 v68, v[2:5] offset:48
	v_cvt_pk_bf16_f32 v64, v58, v59
	v_cvt_pk_bf16_f32 v65, v60, v61
	s_waitcnt lgkmcnt(7)
	v_cvt_pk_bf16_f32 v2, v46, v47
	v_cvt_pk_bf16_f32 v3, v48, v49
	s_waitcnt lgkmcnt(6)
	v_cvt_pk_bf16_f32 v4, v42, v43
	v_cvt_pk_bf16_f32 v5, v44, v45
	ds_write_b128 v68, v[2:5] offset:64
	v_cvt_pk_bf16_f32 v54, v54, v55
	v_cvt_pk_bf16_f32 v55, v56, v57
	s_waitcnt lgkmcnt(3)
	v_cvt_pk_bf16_f32 v2, v38, v39
	v_cvt_pk_bf16_f32 v3, v40, v41
	s_waitcnt lgkmcnt(2)
	v_cvt_pk_bf16_f32 v4, v34, v35
	v_cvt_pk_bf16_f32 v5, v36, v37
	ds_write_b128 v68, v[2:5] offset:80
	v_cvt_pk_bf16_f32 v56, v50, v51
	v_cvt_pk_bf16_f32 v57, v52, v53
	v_cvt_pk_bf16_f32 v2, v6, v7
	v_cvt_pk_bf16_f32 v3, v8, v9
	v_cvt_pk_bf16_f32 v4, v18, v19
	v_cvt_pk_bf16_f32 v5, v20, v21
	ds_write_b128 v68, v[2:5] offset:96
	ds_write_b128 v68, v[62:65]
	ds_write_b128 v68, v[54:57] offset:16
	s_waitcnt lgkmcnt(1)
	v_cvt_pk_bf16_f32 v2, v26, v27
	v_cvt_pk_bf16_f32 v3, v28, v29
	s_waitcnt lgkmcnt(0)
	v_cvt_pk_bf16_f32 v4, v30, v31
	v_cvt_pk_bf16_f32 v5, v32, v33
	ds_write_b128 v68, v[2:5] offset:112
	s_waitcnt lgkmcnt(0)
	s_barrier
	v_lshrrev_b32_e32 v70, 4, v0
	v_lshrrev_b32_e32 v71, 1, v0
	v_mul_u32_u24_e32 v68, 0x210, v70
	v_sub_u32_e32 v70, v70, v71
	v_mul_i32_i24_e32 v70, 0x1400, v70
	v_and_b32_e32 v71, 15, v0
	v_lshl_add_u32 v70, v71, 4, v70
	v_lshl_add_u32 v68, v71, 4, v68
	v_and_b32_e32 v71, 1, v0
	v_lshlrev_b32_e32 v71, 7, v71
	v_sub_u32_e32 v70, v70, v71
	v_ashrrev_i32_e32 v71, 31, v70
	s_mov_b64 s[20:21], 0x14000
	v_lshl_add_u64 v[66:67], v[66:67], 0, v[70:71]
	ds_read_b128 v[2:5], v68
	ds_read_b128 v[6:9], v68 offset:8448
	ds_read_b128 v[10:13], v68 offset:16896
	ds_read_b128 v[14:17], v68 offset:25344
	ds_read_b128 v[18:21], v68 offset:33792
	ds_read_b128 v[22:25], v68 offset:42240
	ds_read_b128 v[26:29], v68 offset:50688
	ds_read_b128 v[30:33], v68 offset:59136
	s_waitcnt lgkmcnt(7)
	global_store_dwordx4 v[66:67], v[2:5], off
	v_lshl_add_u64 v[66:67], v[66:67], 0, s[20:21]
	s_waitcnt lgkmcnt(6)
	global_store_dwordx4 v[66:67], v[6:9], off
	v_lshl_add_u64 v[66:67], v[66:67], 0, s[20:21]
	s_waitcnt lgkmcnt(5)
	global_store_dwordx4 v[66:67], v[10:13], off
	v_lshl_add_u64 v[66:67], v[66:67], 0, s[20:21]
	s_waitcnt lgkmcnt(4)
	global_store_dwordx4 v[66:67], v[14:17], off
	v_lshl_add_u64 v[66:67], v[66:67], 0, s[20:21]
	s_waitcnt lgkmcnt(3)
	global_store_dwordx4 v[66:67], v[18:21], off
	v_lshl_add_u64 v[66:67], v[66:67], 0, s[20:21]
	s_waitcnt lgkmcnt(2)
	global_store_dwordx4 v[66:67], v[22:25], off
	v_lshl_add_u64 v[66:67], v[66:67], 0, s[20:21]
	s_waitcnt lgkmcnt(1)
	global_store_dwordx4 v[66:67], v[26:29], off
	v_lshl_add_u64 v[66:67], v[66:67], 0, s[20:21]
	s_waitcnt lgkmcnt(0)
	global_store_dwordx4 v[66:67], v[30:33], off
	s_mov_b32 s96, 0x800000
	s_cbranch_execnz .LBB0_194
	s_branch .LBB0_247
